# attention s-loop: output-row stores and the first K-fragment base also use SALU-advanced SGPR bases + loop-invariant VGPR offsets (16 more 64-bit VALU address ops and one v_mad_u64_u32 removed per ite
# speedup vs baseline: 1.0074x; 1.0010x over previous
.Lattn_stage_k23:
	global_load_dwordx4 v[12:15], v252, s[86:87] offset:3072
	global_load_dwordx4 v[230:233], v253, s[86:87] offset:3072
	s_mov_b32 s69, 0
	s_lshl_b32 s70, s68, 3
	s_add_i32 s76, s70, s3
	v_or_b32_e32 v2, s66, v124
	v_mov_b64_e32 v[0:1], s[50:51]
	s_lshl_b32 s84, s76, 6
	v_mad_u64_u32 v[0:1], s[70:71], v2, s95, v[0:1]
	s_ashr_i32 s85, s84, 31
	v_mad_i32_i24 v1, s67, v187, v1
	s_lshl_b64 s[70:71], s[84:85], 1
	s_ashr_i32 s77, s76, 31
	v_lshl_add_u64 v[0:1], v[0:1], 0, s[70:71]
	v_lshlrev_b32_e32 v126, 1, v141
	s_lshl_b64 s[76:77], s[76:77], 2
	v_lshl_add_u64 v[0:1], v[0:1], 0, v[126:127]
	s_add_u32 s76, s78, s76
	global_load_dwordx4 v[48:51], v[0:1], off nt
	global_load_dwordx4 v[108:111], v[0:1], off offset:32 nt
	global_load_dwordx4 v[104:107], v[0:1], off offset:64 nt
	global_load_dwordx4 v[120:123], v[0:1], off offset:96 nt
	s_addc_u32 s77, s79, s77
	global_load_dword v16, v127, s[76:77]
	v_lshl_add_u64 v[0:1], s[84:85], 2, v[138:139]
	global_load_dwordx4 v[80:83], v[0:1], off
	global_load_dwordx4 v[84:87], v[0:1], off offset:16
	s_waitcnt vmcnt(8)
	ds_write_b128 v186, v[4:7]
	ds_write_b128 v176, v[8:11]
	ds_write_b128 v177, v[12:15]
	ds_write_b16 v179, v234 offset:36864
	ds_write_b16_d16_hi v179, v234 offset:37392
	ds_write_b16 v179, v235 offset:37920
	ds_write_b16_d16_hi v179, v235 offset:38448
	ds_write_b16 v179, v236 offset:38976
	ds_write_b16_d16_hi v179, v236 offset:39504
	ds_write_b16 v179, v237 offset:40032
	ds_write_b16_d16_hi v179, v237 offset:40560
	ds_write_b16 v180, v238 offset:36864
	ds_write_b16_d16_hi v180, v238 offset:37392
	ds_write_b16 v180, v239 offset:37920
	ds_write_b16_d16_hi v180, v239 offset:38448
	ds_write_b16 v180, v240 offset:38976
	ds_write_b16_d16_hi v180, v240 offset:39504
	ds_write_b16 v180, v241 offset:40032
	ds_write_b16_d16_hi v180, v241 offset:40560
	ds_write_b16 v181, v242 offset:36864
	ds_write_b16_d16_hi v181, v242 offset:37392
	ds_write_b16 v181, v243 offset:37920
	ds_write_b16_d16_hi v181, v243 offset:38448
	ds_write_b16 v181, v244 offset:38976
	ds_write_b16_d16_hi v181, v244 offset:39504
	ds_write_b16 v181, v245 offset:40032
	ds_write_b16_d16_hi v181, v245 offset:40560
	ds_write_b16 v182, v246 offset:36864
	ds_write_b16_d16_hi v182, v246 offset:37392
	ds_write_b16 v182, v247 offset:37920
	ds_write_b16_d16_hi v182, v247 offset:38448
	ds_write_b16 v182, v248 offset:38976
	ds_write_b16_d16_hi v182, v248 offset:39504
	ds_write_b16 v182, v249 offset:40032
	ds_write_b16_d16_hi v182, v249 offset:40560
	s_waitcnt vmcnt(7)
	ds_write_b128 v178, v[230:233]
	s_waitcnt lgkmcnt(0)
	s_barrier
	s_mul_i32 s85, s72, 0x9000000
	s_cmp_eq_u32 s99, 0
	s_mul_hi_i32 s84, s72, 0x9000000
	v_lshl_add_u64 v[0:1], v[124:125], 0, s[74:75]
	s_cselect_b64 s[72:73], -1, 0
	s_add_u32 s74, s70, s85
	s_addc_u32 s75, s71, s84
	v_mov_b64_e32 v[2:3], s[74:75]
	v_mad_u64_u32 v[2:3], s[74:75], v0, s95, v[2:3]
	v_mad_i32_i24 v3, v1, s95, v3
	v_mov_b32_e32 v151, v173
	v_mov_b32_e32 v153, v172
	s_mov_b32 s76, 0
	s_mov_b32 s77, 0
	v_lshl_add_u64 v[162:163], v[142:143], 0, s[70:71]
	v_lshl_add_u64 v[164:165], v[148:149], 0, v[2:3]
	s_waitcnt vmcnt(6)
	v_mov_b64_e32 v[90:91], v[50:51]
	s_waitcnt vmcnt(5)
	v_mov_b64_e32 v[92:93], v[108:109]
	s_waitcnt vmcnt(4)
	v_mov_b64_e32 v[96:97], v[104:105]
	s_waitcnt vmcnt(3)
	v_mov_b64_e32 v[100:101], v[120:121]
	v_mov_b64_e32 v[88:89], v[48:49]
	v_mov_b64_e32 v[94:95], v[110:111]
	v_mov_b64_e32 v[98:99], v[106:107]
	v_mov_b64_e32 v[102:103], v[122:123]
	s_waitcnt vmcnt(2)
	v_mul_f32_e32 v155, 0x3fb8aa3b, v16
	v_mul_u32_u24_e32 v231, 0x2400, v145
	v_add_u32_e32 v231, v231, v160
	v_add_u32_e32 v232, 0x12000, v231
	v_add_u32_e32 v233, 0x24000, v231
	v_add_u32_e32 v234, 0x36000, v231
	v_lshl_add_u32 v235, v145, 12, v160
	v_add_u32_e32 v236, 0x8000, v235
	v_add_u32_e32 v237, 0x10000, v235
	v_add_u32_e32 v238, 0x18000, v235
	v_mul_u32_u24_e32 v239, 0x90, v124
	v_add_u32_e32 v239, v239, v140
	s_branch .LBB0_315
.LBB0_314:
	s_or_b64 exec, exec, s[74:75]
	s_add_u32 s100, s66, s84
	s_lshl_b32 s100, s100, 12
	s_add_u32 s100, s100, s62
	s_addc_u32 s101, s63, 0
	s_add_u32 s100, s100, s70
	s_addc_u32 s101, s101, s71
	s_add_u32 s100, s100, 0x4000000
	s_addc_u32 s101, s101, 0
	v_cvt_pk_bf16_f32 v0, v0, v1
	v_cvt_pk_bf16_f32 v1, v2, v3
	v_cvt_pk_bf16_f32 v2, v4, v5
	v_cvt_pk_bf16_f32 v3, v6, v7
	ds_write2_b64 v183, v[0:1], v[2:3] offset1:2
	v_cvt_pk_bf16_f32 v0, v8, v9
	v_cvt_pk_bf16_f32 v1, v10, v11
	v_cvt_pk_bf16_f32 v2, v12, v13
	v_cvt_pk_bf16_f32 v3, v32, v33
	ds_write2_b64 v183, v[0:1], v[2:3] offset0:4 offset1:6
	v_cvt_pk_bf16_f32 v0, v14, v15
	v_cvt_pk_bf16_f32 v1, v16, v17
	v_cvt_pk_bf16_f32 v2, v18, v19
	v_cvt_pk_bf16_f32 v3, v20, v21
	ds_write2_b64 v183, v[0:1], v[2:3] offset0:8 offset1:10
	v_cvt_pk_bf16_f32 v0, v22, v23
	v_cvt_pk_bf16_f32 v1, v24, v25
	v_cvt_pk_bf16_f32 v2, v26, v27
	v_cvt_pk_bf16_f32 v3, v28, v29
	ds_write2_b64 v183, v[0:1], v[2:3] offset0:12 offset1:14
	s_waitcnt lgkmcnt(0)
	ds_read_b128 v[0:3], v184
	ds_read_b128 v[4:7], v184 offset:1152
	s_waitcnt vmcnt(3)
	v_lshlrev_b32_e32 v10, 16, v116
	v_and_b32_e32 v11, 0xffff0000, v116
	s_waitcnt lgkmcnt(1)
	v_lshlrev_b32_e32 v8, 16, v0
	v_and_b32_e32 v9, 0xffff0000, v0
	v_pk_mul_f32 v[8:9], v[80:81], v[8:9]
	s_waitcnt vmcnt(1)
	v_lshlrev_b32_e32 v12, 16, v108
	v_pk_mul_f32 v[8:9], v[8:9], v[10:11]
	v_lshlrev_b32_e32 v10, 16, v117
	v_cvt_pk_bf16_f32 v0, v8, v9
	v_lshlrev_b32_e32 v8, 16, v1
	v_and_b32_e32 v9, 0xffff0000, v1
	v_pk_mul_f32 v[8:9], v[82:83], v[8:9]
	v_and_b32_e32 v11, 0xffff0000, v117
	v_pk_mul_f32 v[8:9], v[8:9], v[10:11]
	v_lshlrev_b32_e32 v10, 16, v118
	v_cvt_pk_bf16_f32 v1, v8, v9
	v_lshlrev_b32_e32 v8, 16, v2
	v_and_b32_e32 v9, 0xffff0000, v2
	v_pk_mul_f32 v[8:9], v[84:85], v[8:9]
	v_and_b32_e32 v11, 0xffff0000, v118
	v_pk_mul_f32 v[8:9], v[8:9], v[10:11]
	v_lshlrev_b32_e32 v10, 16, v119
	v_cvt_pk_bf16_f32 v2, v8, v9
	v_lshlrev_b32_e32 v8, 16, v3
	v_and_b32_e32 v9, 0xffff0000, v3
	v_pk_mul_f32 v[8:9], v[86:87], v[8:9]
	v_and_b32_e32 v11, 0xffff0000, v119
	v_pk_mul_f32 v[8:9], v[8:9], v[10:11]
	v_and_b32_e32 v13, 0xffff0000, v108
	v_cvt_pk_bf16_f32 v3, v8, v9
	global_store_dwordx4 v235, v[0:3], s[100:101]
	s_nop 1
	s_waitcnt lgkmcnt(0)
	v_lshlrev_b32_e32 v0, 16, v4
	v_and_b32_e32 v1, 0xffff0000, v4
	v_pk_mul_f32 v[0:1], v[80:81], v[0:1]
	v_lshlrev_b32_e32 v2, 16, v112
	v_and_b32_e32 v3, 0xffff0000, v112
	v_pk_mul_f32 v[0:1], v[0:1], v[2:3]
	v_lshlrev_b32_e32 v2, 16, v5
	v_and_b32_e32 v3, 0xffff0000, v5
	v_pk_mul_f32 v[2:3], v[82:83], v[2:3]
	v_lshlrev_b32_e32 v4, 16, v113
	v_and_b32_e32 v5, 0xffff0000, v113
	v_pk_mul_f32 v[2:3], v[2:3], v[4:5]
	v_cvt_pk_bf16_f32 v0, v0, v1
	v_cvt_pk_bf16_f32 v1, v2, v3
	v_lshlrev_b32_e32 v2, 16, v6
	v_and_b32_e32 v3, 0xffff0000, v6
	v_pk_mul_f32 v[2:3], v[84:85], v[2:3]
	v_lshlrev_b32_e32 v4, 16, v114
	v_and_b32_e32 v5, 0xffff0000, v114
	v_pk_mul_f32 v[2:3], v[2:3], v[4:5]
	v_lshlrev_b32_e32 v4, 16, v7
	v_and_b32_e32 v5, 0xffff0000, v7
	v_pk_mul_f32 v[4:5], v[86:87], v[4:5]
	v_lshlrev_b32_e32 v6, 16, v115
	v_and_b32_e32 v7, 0xffff0000, v115
	v_pk_mul_f32 v[4:5], v[4:5], v[6:7]
	v_cvt_pk_bf16_f32 v2, v2, v3
	v_cvt_pk_bf16_f32 v3, v4, v5
	ds_read_b128 v[4:7], v184 offset:2304
	global_store_dwordx4 v236, v[0:3], s[100:101]
	ds_read_b128 v[0:3], v184 offset:3456
	s_waitcnt lgkmcnt(1)
	v_lshlrev_b32_e32 v10, 16, v4
	v_and_b32_e32 v11, 0xffff0000, v4
	v_pk_mul_f32 v[10:11], v[80:81], v[10:11]
	v_pk_mul_f32 v[10:11], v[10:11], v[12:13]
	v_lshlrev_b32_e32 v12, 16, v109
	v_cvt_pk_bf16_f32 v4, v10, v11
	v_lshlrev_b32_e32 v10, 16, v5
	v_and_b32_e32 v11, 0xffff0000, v5
	v_pk_mul_f32 v[10:11], v[82:83], v[10:11]
	v_and_b32_e32 v13, 0xffff0000, v109
	v_pk_mul_f32 v[10:11], v[10:11], v[12:13]
	v_lshlrev_b32_e32 v12, 16, v110
	v_cvt_pk_bf16_f32 v5, v10, v11
	v_lshlrev_b32_e32 v10, 16, v6
	v_and_b32_e32 v11, 0xffff0000, v6
	v_pk_mul_f32 v[10:11], v[84:85], v[10:11]
	v_and_b32_e32 v13, 0xffff0000, v110
	v_pk_mul_f32 v[10:11], v[10:11], v[12:13]
	v_lshlrev_b32_e32 v12, 16, v111
	v_cvt_pk_bf16_f32 v6, v10, v11
	v_lshlrev_b32_e32 v10, 16, v7
	v_and_b32_e32 v11, 0xffff0000, v7
	v_pk_mul_f32 v[10:11], v[86:87], v[10:11]
	v_and_b32_e32 v13, 0xffff0000, v111
	v_pk_mul_f32 v[10:11], v[10:11], v[12:13]
	v_cvt_pk_bf16_f32 v7, v10, v11
	global_store_dwordx4 v237, v[4:7], s[100:101]
	s_waitcnt vmcnt(3)
	v_lshlrev_b32_e32 v8, 16, v104
	v_and_b32_e32 v9, 0xffff0000, v104
	s_waitcnt lgkmcnt(0)
	v_lshlrev_b32_e32 v6, 16, v0
	v_and_b32_e32 v7, 0xffff0000, v0
	v_pk_mul_f32 v[6:7], v[80:81], v[6:7]
	v_pk_mul_f32 v[6:7], v[6:7], v[8:9]
	v_lshlrev_b32_e32 v8, 16, v105
	v_cvt_pk_bf16_f32 v0, v6, v7
	v_lshlrev_b32_e32 v6, 16, v1
	v_and_b32_e32 v7, 0xffff0000, v1
	v_pk_mul_f32 v[6:7], v[82:83], v[6:7]
	v_and_b32_e32 v9, 0xffff0000, v105
	v_pk_mul_f32 v[6:7], v[6:7], v[8:9]
	v_lshlrev_b32_e32 v8, 16, v106
	v_cvt_pk_bf16_f32 v1, v6, v7
	v_lshlrev_b32_e32 v6, 16, v2
	v_and_b32_e32 v7, 0xffff0000, v2
	v_pk_mul_f32 v[6:7], v[84:85], v[6:7]
	v_and_b32_e32 v9, 0xffff0000, v106
	v_pk_mul_f32 v[6:7], v[6:7], v[8:9]
	v_lshlrev_b32_e32 v8, 16, v107
	v_cvt_pk_bf16_f32 v2, v6, v7
	v_lshlrev_b32_e32 v6, 16, v3
	v_and_b32_e32 v7, 0xffff0000, v3
	v_pk_mul_f32 v[6:7], v[86:87], v[6:7]
	v_and_b32_e32 v9, 0xffff0000, v107
	v_pk_mul_f32 v[6:7], v[6:7], v[8:9]
	v_cvt_pk_bf16_f32 v3, v6, v7
	global_store_dwordx4 v238, v[0:3], s[100:101]
	s_waitcnt lgkmcnt(0)
	s_add_i32 s76, s76, 32
	s_add_i32 s69, s69, 64
	s_add_i32 s77, s77, 1
	v_mov_b64_e32 v[48:49], v[88:89]
	v_mov_b64_e32 v[110:111], v[94:95]
	v_mov_b64_e32 v[106:107], v[98:99]
	v_mov_b64_e32 v[122:123], v[102:103]
	v_add_u32_e32 v153, 0x1200, v153
	v_lshl_add_u64 v[164:165], v[164:165], 0, s[56:57]
	v_add_u32_e32 v151, 0x80, v151
	s_cmpk_eq_i32 s69, 0x100
	v_mov_b64_e32 v[50:51], v[90:91]
	v_mov_b64_e32 v[108:109], v[92:93]
	v_mov_b64_e32 v[104:105], v[96:97]
	v_mov_b64_e32 v[120:121], v[100:101]
	s_cbranch_scc1 .LBB0_322

.LBB0_317:
	s_mul_i32 s100, s84, 0x90
	v_add_u32_e32 v8, s100, v239
	s_add_u32 s100, s66, s84
	s_mul_i32 s100, s100, 0x2400
	s_add_u32 s100, s100, s50
	s_addc_u32 s101, s51, 0
	s_add_u32 s100, s100, s70
	s_addc_u32 s101, s101, s71
	s_add_u32 s100, s100, 0x1000
	s_addc_u32 s101, s101, 0
	ds_read_b128 v[0:3], v8
	ds_read_b128 v[4:7], v8 offset:32
	s_waitcnt lgkmcnt(1)
	v_mfma_f32_32x32x16_bf16 v[64:79], v[0:3], v[48:51], 0
	s_waitcnt lgkmcnt(0)
	v_mfma_f32_32x32x16_bf16 v[64:79], v[4:7], v[108:111], v[64:79]
	ds_read_b128 v[0:3], v8 offset:64
	ds_read_b128 v[4:7], v8 offset:96
	s_waitcnt lgkmcnt(1)
	v_mfma_f32_32x32x16_bf16 v[64:79], v[0:3], v[104:107], v[64:79]
	s_waitcnt lgkmcnt(0)
	v_mfma_f32_32x32x16_bf16 v[64:79], v[4:7], v[120:123], v[64:79]
	ds_read_b128 v[0:3], v153
	ds_read_b128 v[4:7], v153 offset:32
	s_waitcnt lgkmcnt(1)
	v_mfma_f32_32x32x16_bf16 v[32:47], v[0:3], v[48:51], 0
	s_waitcnt lgkmcnt(0)
	v_mfma_f32_32x32x16_bf16 v[32:47], v[4:7], v[108:111], v[32:47]
	ds_read_b128 v[0:3], v153 offset:64
	ds_read_b128 v[4:7], v153 offset:96
	s_waitcnt lgkmcnt(1)
	v_mfma_f32_32x32x16_bf16 v[32:47], v[0:3], v[104:107], v[32:47]
	s_waitcnt lgkmcnt(0)
	v_mfma_f32_32x32x16_bf16 v[32:47], v[4:7], v[120:123], v[32:47]
	ds_read_b128 v[0:3], v153 offset:4608
	ds_read_b128 v[4:7], v153 offset:4640
	ds_read_b128 v[52:55], v153 offset:9248
	s_waitcnt lgkmcnt(2)
	v_mfma_f32_32x32x16_bf16 v[16:31], v[0:3], v[48:51], 0
	ds_read_b128 v[0:3], v153 offset:4672
	s_waitcnt lgkmcnt(2)
	v_mfma_f32_32x32x16_bf16 v[16:31], v[4:7], v[108:111], v[16:31]
	ds_read_b128 v[4:7], v153 offset:4704
	s_waitcnt lgkmcnt(1)
	v_mfma_f32_32x32x16_bf16 v[16:31], v[0:3], v[104:107], v[16:31]
	ds_read_b128 v[0:3], v153 offset:9216
	s_waitcnt lgkmcnt(1)
	v_mfma_f32_32x32x16_bf16 v[16:31], v[4:7], v[120:123], v[16:31]
	s_waitcnt lgkmcnt(0)
	v_mfma_f32_32x32x16_bf16 v[0:15], v[0:3], v[48:51], 0
	ds_read_b128 v[56:59], v153 offset:9280
	v_mfma_f32_32x32x16_bf16 v[0:15], v[52:55], v[108:111], v[0:15]
	global_load_dwordx4 v[116:119], v231, s[100:101] nt
	global_load_dwordx4 v[112:115], v232, s[100:101] nt
	ds_read_b128 v[52:55], v153 offset:9312
	ds_read_b128 v[198:201], v153 offset:13856
	s_waitcnt lgkmcnt(2)
	v_mfma_f32_32x32x16_bf16 v[0:15], v[56:59], v[104:107], v[0:15]
	ds_read_b128 v[56:59], v153 offset:13824
	s_waitcnt lgkmcnt(2)
	v_mfma_f32_32x32x16_bf16 v[0:15], v[52:55], v[120:123], v[0:15]
	ds_read_b128 v[202:205], v153 offset:13888
	s_waitcnt lgkmcnt(1)
	v_mfma_f32_32x32x16_bf16 v[48:63], v[56:59], v[48:51], 0
	v_mfma_f32_32x32x16_bf16 v[48:63], v[198:201], v[108:111], v[48:63]
	ds_read_b128 v[198:201], v153 offset:13920
	s_andn2_b64 vcc, exec, s[72:73]
	s_waitcnt lgkmcnt(1)
	v_mfma_f32_32x32x16_bf16 v[48:63], v[202:205], v[104:107], v[48:63]
	global_load_dwordx4 v[108:111], v233, s[100:101] nt
	global_load_dwordx4 v[104:107], v234, s[100:101] nt
	s_waitcnt lgkmcnt(0)
	v_mfma_f32_32x32x16_bf16 v[48:63], v[198:201], v[120:123], v[48:63]
	s_cbranch_vccz .LBB0_319
	v_cndmask_b32_e64 v120, v188, v64, s[8:9]
	v_cndmask_b32_e64 v189, v65, v188, s[10:11]
	v_cndmask_b32_e64 v161, v188, v66, s[12:13]
	v_cndmask_b32_e64 v159, v188, v67, s[14:15]
	v_cndmask_b32_e64 v157, v188, v68, s[16:17]
	v_cndmask_b32_e64 v126, v188, v69, s[18:19]
	v_cndmask_b32_e64 v123, v188, v70, s[20:21]
	v_cndmask_b32_e64 v122, v188, v71, s[22:23]
	v_cndmask_b32_e64 v121, v188, v72, s[24:25]
	v_cndmask_b32_e64 v73, v188, v73, s[26:27]
	v_cndmask_b32_e64 v72, v188, v74, s[28:29]
	v_cndmask_b32_e64 v71, v188, v75, s[30:31]
	v_cndmask_b32_e64 v70, v188, v76, s[34:35]
	v_cndmask_b32_e64 v69, v188, v77, s[36:37]
	v_cndmask_b32_e64 v68, v188, v78, s[38:39]
	v_cndmask_b32_e64 v67, v188, v79, s[40:41]
	s_branch .LBB0_320

.LBB0_522:
	s_nop 0
	s_nop 0
	s_nop 0
	s_nop 0
	s_nop 0
	s_cmp_lt_i32 s80, 7
	s_cselect_b64 s[0:1], -1, 0
	s_cmp_gt_i32 s81, 6
	s_cselect_b64 s[4:5], -1, 0
	s_and_b64 s[0:1], s[0:1], s[4:5]
	s_andn2_b64 vcc, exec, s[0:1]
	s_cbranch_vccnz .LBB0_622
	v_lshrrev_b32_e32 v2, 1, v144
	v_lshrrev_b32_e32 v3, 5, v144
	v_and_b32_e32 v2, 24, v2
	v_and_b32_e32 v3, 4, v3
	v_bfe_u32 v4, v144, 2, 2
	v_lshlrev_b32_e32 v0, 4, v144
	v_and_b32_e32 v1, 32, v144
	v_bfe_u32 v10, v144, 2, 4
	v_or3_b32 v2, v3, v4, v2
	v_lshrrev_b32_e32 v3, 3, v144
	s_movk_i32 s0, 0x70
	v_bitop3_b32 v8, v0, v1, 48 bitop3:0x6c
	v_and_b32_e32 v9, 64, v144
	v_and_or_b32 v4, v3, s0, v10
	s_movk_i32 s0, 0x60
	v_add_u32_e32 v11, 0x2000, v0
	v_or_b32_e32 v1, v8, v9
	v_and_or_b32 v3, v3, s0, v2
	v_lshrrev_b32_e32 v0, 7, v11
	s_movk_i32 s0, 0xf0
	s_add_u32 s30, s62, 0x4000000
	v_lshl_or_b32 v150, v4, 12, v1
	v_and_or_b32 v3, v0, s0, v10
	s_movk_i32 s0, 0xe0
	s_addc_u32 s31, s63, 0
	v_and_or_b32 v0, v0, s0, v2
	s_lshl_b32 s0, s2, 2
	s_and_b32 s0, s0, 28
	s_ashr_i32 s1, s2, 6
	s_add_i32 s0, s0, s1
	s_waitcnt lgkmcnt(0)
	s_bfe_u32 s16, s2, 0x30003
	s_ashr_i32 s1, s0, 31
	s_lshl_b64 s[6:7], s[0:1], 20
	s_lshl_b32 s2, s16, 20
	s_add_u32 s1, s62, s2
	s_addc_u32 s3, s63, 0
	s_add_u32 s4, s1, 0x1200000
	s_addc_u32 s5, s3, 0
	s_add_u32 s8, s1, 0x1280000
	s_addc_u32 s9, s3, 0
	s_add_u32 s6, s30, s6
	s_addc_u32 s7, s31, s7
	s_add_u32 s10, s6, 0x80000
	v_readfirstlane_b32 s3, v144
	s_addc_u32 s11, s7, 0
	s_lshr_b32 s18, s3, 6
	s_lshl_b32 s1, s18, 10
	s_add_i32 s34, s1, 0
	s_add_i32 m0, s34, 0x10000
	v_lshl_or_b32 v154, v3, 12, v1
	global_load_lds_dwordx4 v150, s[4:5]
	s_add_i32 m0, s34, 0x12000
	v_lshl_or_b32 v148, v4, 12, v1
	global_load_lds_dwordx4 v154, s[4:5]
	s_add_i32 m0, s34, 0x14000
	s_add_i32 s35, s34, 0x2000
	global_load_lds_dwordx4 v150, s[8:9]
	s_add_i32 m0, s34, 0x16000
	v_lshl_or_b32 v152, v3, 12, v1
	global_load_lds_dwordx4 v154, s[8:9]
	s_mov_b32 m0, s34
	s_add_i32 s36, s34, 0x4000
	global_load_lds_dwordx4 v148, s[6:7]
	s_mov_b32 m0, s35
	s_add_i32 s37, s34, 0x6000
	global_load_lds_dwordx4 v152, s[6:7]
	s_mov_b32 m0, s36
	v_mov_b32_e32 v151, 0
	global_load_lds_dwordx4 v148, s[10:11]
	s_mov_b32 m0, s37
	s_lshr_b32 s19, s3, 8
	global_load_lds_dwordx4 v152, s[10:11]
	v_mov_b32_e32 v155, v151
	v_mov_b32_e32 v149, v151
	v_mov_b32_e32 v153, v151
	s_cmp_eq_u32 s19, 1
	s_mov_b32 s38, 0
	v_lshl_add_u64 v[0:1], s[4:5], 0, v[150:151]
	v_lshl_add_u64 v[2:3], s[4:5], 0, v[154:155]
	v_lshl_add_u64 v[4:5], s[6:7], 0, v[148:149]
	s_cselect_b64 s[8:9], -1, 0
	s_cmp_lg_u32 s19, 1
	v_lshl_add_u64 v[6:7], s[6:7], 0, v[152:153]
	s_cbranch_scc1 .LBB0_525
	s_barrier
